# ph3 row loop: the two row-invariant norm-gain vectors are loaded once before the loop instead of being re-loaded and waited on for every row
# speedup vs baseline: 1.0477x; 1.0054x over previous
; #define GAS __attribute__((address_space(1)))
; __global__ void __launch_bounds__(256, 2) fwd_kernel(Params p) {
;     ...
;       const float* gq = pp->in[13]; const float* gkv = pp->in[15];
;       for (int row = gw; row < NT; row += NW) {
;         unsigned wq[3], wk[2], d0[2], d1[2], kr0 = 0, kr1 = 0;
;         f32x4 cd[2], ck = {0.f, 0.f, 0.f, 0.f};
;         const bool lat = row < NL;
;         const int t = row & 2047;
;         bf16_t* pr = P + (size_t)row * PLD;
; #pragma unroll
;         for (int i = 0; i < 3; ++i) wq[i] = *(const GAS unsigned*)(pr + PE_CQ + 2 * lane + 128 * i);
; #pragma unroll
;         for (int i = 0; i < 2; ++i) wk[i] = *(const GAS unsigned*)(pr + PE_CKV + 2 * lane + 128 * i);
;         if (lat) {
; #pragma unroll
;           for (int u = 0; u < 2; ++u) {
;             const int dp = lane + 64 * u, grp = dp >> 4, i2 = (dp & 15) * 2;
;             d0[u] = *(const GAS unsigned*)(pr + PE_DK + grp * 64 + i2);
;             d1[u] = *(const GAS unsigned*)(pr + PE_DK + grp * 64 + i2 + 32);
;             cd[u] = *(const GAS f32x4*)((const float*)(CS64 + t * 32 + i2));
;           }
;           if (lane < 8) {
;             kr0 = *(const GAS unsigned*)(pr + PE_KR + 2 * lane);
;             kr1 = *(const GAS unsigned*)(pr + PE_KR + 2 * lane + 16);
;             ck = *(const GAS f32x4*)((const float*)(CS32 + t * 16 + 2 * lane));
;           }
;         }
;         f32x2 g2q[3], g2k[2];
; #pragma unroll
;         for (int i = 0; i < 3; ++i) g2q[i] = *(const GAS f32x2*)(gq + 2 * lane + 128 * i);
; #pragma unroll
;         for (int i = 0; i < 2; ++i) g2k[i] = *(const GAS f32x2*)(gkv + 2 * lane + 128 * i);
.LBB0_155:
	v_readlane_b32 s10, v252, 11
	s_add_i32 s77, s62, s10
	s_and_b64 vcc, exec, s[12:13]
	v_writelane_b32 v250, s62, 21
	s_cbranch_vccz .LBB0_200
	v_readlane_b32 s10, v250, 20
	s_cmp_gt_i32 s10, 1
	s_mov_b64 s[12:13], -1
	s_cbranch_scc0 .LBB0_170
	v_readlane_b32 s10, v250, 20
	s_cmp_gt_i32 s10, 2
	s_cbranch_scc0 .LBB0_180
	v_mov_b64_e32 v[6:7], v[130:131]
	v_mov_b64_e32 v[2:3], v[134:135]
	s_cmp_gt_i32 s77, 0x11fff
	v_mov_b32_e32 v31, v214
	v_mov_b32_e32 v30, v215
	v_mov_b32_e32 v29, v216
	v_mov_b32_e32 v28, v217
	v_mov_b64_e32 v[8:9], v[132:133]
	v_mov_b64_e32 v[4:5], v[136:137]
	s_cbranch_scc1 .LBB0_179
	s_load_dwordx2 s[12:13], s[8:9], 0x68
	s_load_dwordx2 s[14:15], s[8:9], 0x78
	v_lshlrev_b32_e32 v0, 4, v188
	v_readlane_b32 s16, v250, 18
	v_and_b32_e32 v0, 0xf0, v0
	v_readlane_b32 s17, v250, 19
	s_mov_b64 s[10:11], 0x309f600
	v_mov_b64_e32 v[6:7], v[130:131]
	v_lshl_add_u64 v[2:3], s[16:17], 0, v[0:1]
	v_lshlrev_b32_e32 v0, 4, v190
	v_lshl_add_u64 v[14:15], v[2:3], 0, s[10:11]
	v_lshl_add_u64 v[2:3], s[16:17], 0, v[0:1]
	v_lshlrev_b32_e32 v0, 3, v190
	s_mov_b64 s[10:11], 0x311f600
	s_waitcnt lgkmcnt(0)
	v_lshl_add_u64 v[18:19], s[12:13], 0, v[0:1]
	v_lshl_add_u64 v[20:21], s[14:15], 0, v[0:1]
	global_load_dwordx2 v[226:227], v[18:19], off
	global_load_dwordx2 v[228:229], v[18:19], off offset:512
	global_load_dwordx2 v[230:231], v[18:19], off offset:1024
	global_load_dwordx2 v[232:233], v[20:21], off
	global_load_dwordx2 v[234:235], v[20:21], off offset:512
	v_and_b32_e32 v0, 64, v202
	v_lshl_add_u64 v[16:17], v[2:3], 0, s[10:11]
	v_add_u32_e32 v0, 64, v0
	v_xor_b32_e32 v2, 32, v202
	v_cmp_lt_i32_e32 vcc, v2, v0
	s_movk_i32 s10, 0x180
	s_mul_i32 s11, s77, 0x1200
	v_cndmask_b32_e32 v2, v202, v2, vcc
	v_lshlrev_b32_e32 v32, 2, v2
	v_xor_b32_e32 v2, 16, v202
	v_cmp_lt_i32_e32 vcc, v2, v0
	s_add_u32 s12, s16, s11
	v_cmp_gt_u32_e64 s[40:41], 8, v190
	v_cndmask_b32_e32 v2, v202, v2, vcc
	v_lshlrev_b32_e32 v33, 2, v2
	v_xor_b32_e32 v2, 8, v202
	v_cmp_lt_i32_e32 vcc, v2, v0
	v_lshlrev_b32_e32 v22, 2, v190
	v_mov_b32_e32 v23, v1
	v_cndmask_b32_e32 v2, v202, v2, vcc
	v_lshlrev_b32_e32 v34, 2, v2
	v_xor_b32_e32 v2, 4, v202
	v_cmp_lt_i32_e32 vcc, v2, v0
	v_mov_b64_e32 v[8:9], v[132:133]
	v_mov_b32_e32 v28, v217
	v_cndmask_b32_e32 v2, v202, v2, vcc
	v_lshlrev_b32_e32 v35, 2, v2
	v_xor_b32_e32 v2, 2, v202
	v_cmp_lt_i32_e32 vcc, v2, v0
	v_mov_b32_e32 v29, v216
	v_mov_b32_e32 v30, v215
	v_cndmask_b32_e32 v2, v202, v2, vcc
	v_lshlrev_b32_e32 v36, 2, v2
	v_xor_b32_e32 v2, 1, v202
	v_cmp_lt_i32_e32 vcc, v2, v0
	v_mov_b32_e32 v31, v214
	s_mov_b32 s18, s77
	v_cndmask_b32_e32 v0, v202, v2, vcc
	v_and_b32_e32 v2, 15, v188
	v_lshlrev_b32_e32 v37, 2, v0
	v_lshlrev_b32_e32 v0, 3, v188
	v_lshlrev_b32_e32 v2, 2, v2
	v_and_or_b32 v0, v0, s10, v2
	s_mul_hi_i32 s10, s77, 0x1200
	v_mov_b64_e32 v[2:3], v[134:135]
	s_addc_u32 s13, s17, s10
	v_mov_b64_e32 v[4:5], v[136:137]
	s_branch .LBB0_162

; #define GAS __attribute__((address_space(1)))
; DI unsigned pk2(float a, float b) { f32x2 v = {a, b}; bf2_t r = __builtin_convertvector(v, bf2_t); return __builtin_bit_cast(unsigned, r); }
; DI float bflo(unsigned w) { return __uint_as_float(w << 16); }
; DI float bfhi(unsigned w) { return __uint_as_float(w & 0xffff0000u); }
; __global__ void __launch_bounds__(256, 2) fwd_kernel(Params p) {
;     ...
;         float ss = 0.f;
; #pragma unroll
;         for (int i = 0; i < 3; ++i) { const float a = bflo(wq[i]), bq = bfhi(wq[i]); ss += a * a + bq * bq; }
;         const float rq = rsqrtf(wave_sum(ss) * (1.f / 384.f) + 1e-6f);
;         float s2 = 0.f;
; #pragma unroll
;         for (int i = 0; i < 2; ++i) { const float a = bflo(wk[i]), bq = bfhi(wk[i]); s2 += a * a + bq * bq; }
;         const float rk = rsqrtf(wave_sum(s2) * (1.f / 256.f) + 1e-6f);
; #pragma unroll
;         for (int i = 0; i < 3; ++i) *(GAS unsigned*)(pr + PE_CQ + 2 * lane + 128 * i) = pk2(bflo(wq[i]) * rq * g2q[i].x, bfhi(wq[i]) * rq * g2q[i].y);
; #pragma unroll
;         for (int i = 0; i < 2; ++i) *(GAS unsigned*)(pr + PE_CKV + 2 * lane + 128 * i) = pk2(bflo(wk[i]) * rk * g2k[i].x, bfhi(wk[i]) * rk * g2k[i].y);
;         if (lat) {
; #pragma unroll
;           for (int u = 0; u < 2; ++u) {
;             const int dp = lane + 64 * u, grp = dp >> 4, i2 = (dp & 15) * 2;
;             const float xa0 = bflo(d0[u]), xa1 = bfhi(d0[u]), xb0 = bflo(d1[u]), xb1 = bfhi(d1[u]);
;             const f32x4 c4 = cd[u];
;             *(GAS unsigned*)(pr + PE_DK + grp * 64 + i2) = pk2(xa0 * c4[0] - xb0 * c4[1], xa1 * c4[2] - xb1 * c4[3]);
;             *(GAS unsigned*)(pr + PE_DK + grp * 64 + i2 + 32) = pk2(xa0 * c4[1] + xb0 * c4[0], xa1 * c4[3] + xb1 * c4[2]);
;           }
;           if (lane < 8) {
;             const float xa0 = bflo(kr0), xa1 = bfhi(kr0), xb0 = bflo(kr1), xb1 = bfhi(kr1);
;             *(GAS unsigned*)(pr + PE_KR + 2 * lane) = pk2(xa0 * ck[0] - xb0 * ck[1], xa1 * ck[2] - xb1 * ck[3]);
;             *(GAS unsigned*)(pr + PE_KR + 2 * lane + 16) = pk2(xa0 * ck[1] + xb0 * ck[0], xa1 * ck[3] + xb1 * ck[2]);
;           }
.LBB0_167:
	s_waitcnt vmcnt(0)
	v_and_b32_e32 v57, 0xffff0000, v44
	s_waitcnt vmcnt(7)
	v_and_b32_e32 v59, 0xffff0000, v42
	v_lshlrev_b32_e32 v56, 16, v44
	v_lshlrev_b32_e32 v44, 16, v43
	v_and_b32_e32 v45, 0xffff0000, v43
	v_lshlrev_b32_e32 v58, 16, v42
	s_waitcnt vmcnt(6)
	v_and_b32_e32 v43, 0xffff0000, v41
	s_waitcnt vmcnt(5)
	v_and_b32_e32 v61, 0xffff0000, v40
	v_mov_b32_e32 v64, v57
	v_mov_b32_e32 v65, v59
	v_lshlrev_b32_e32 v42, 16, v41
	v_lshlrev_b32_e32 v60, 16, v40
	v_mul_f32_e32 v40, v45, v45
	v_mov_b32_e32 v62, v56
	v_mov_b32_e32 v63, v58
	v_pk_mul_f32 v[64:65], v[64:65], v[64:65]
	v_mov_b32_e32 v66, v43
	v_mov_b32_e32 v67, v61
	v_pk_fma_f32 v[40:41], v[44:45], v[44:45], v[40:41] op_sel_hi:[1,1,0]
	v_pk_fma_f32 v[62:63], v[62:63], v[62:63], v[64:65]
	v_mov_b32_e32 v64, v42
	v_mov_b32_e32 v65, v60
	v_pk_mul_f32 v[66:67], v[66:67], v[66:67]
	v_pk_add_f32 v[40:41], v[62:63], v[40:41]
	v_pk_fma_f32 v[64:65], v[64:65], v[64:65], v[66:67]
	v_mov_b32_e32 v67, v40
	v_mov_b32_e32 v66, v64
	v_mov_b32_e32 v62, v65
	v_pk_add_f32 v[40:41], v[66:67], v[62:63]
	ds_bpermute_b32 v63, v32, v41
	ds_bpermute_b32 v62, v32, v40
	s_mov_b64 s[10:11], 0xe960600
	v_lshl_add_u64 v[64:65], v[24:25], 0, s[10:11]
	s_mov_b32 s10, 0x3b800000
	s_mov_b32 s11, 0x3b2aaaab
	s_waitcnt lgkmcnt(0)
	v_pk_add_f32 v[40:41], v[40:41], v[62:63]
	ds_bpermute_b32 v63, v33, v41
	ds_bpermute_b32 v62, v33, v40
	s_mov_b64 s[16:17], 0xe960700
	v_lshl_add_u64 v[66:67], v[24:25], 0, s[16:17]
	s_mov_b64 s[16:17], 0xe960800
	v_lshl_add_u64 v[68:69], v[24:25], 0, s[16:17]
	s_waitcnt lgkmcnt(0)
	v_pk_add_f32 v[40:41], v[40:41], v[62:63]
	ds_bpermute_b32 v63, v34, v41
	ds_bpermute_b32 v62, v34, v40
	s_mov_b64 s[16:17], 0xe960900
	s_waitcnt lgkmcnt(0)
	v_pk_add_f32 v[40:41], v[40:41], v[62:63]
	ds_bpermute_b32 v63, v35, v41
	ds_bpermute_b32 v62, v35, v40
	s_waitcnt lgkmcnt(0)
	v_pk_add_f32 v[40:41], v[40:41], v[62:63]
	ds_bpermute_b32 v63, v36, v41
	ds_bpermute_b32 v62, v36, v40
	s_waitcnt lgkmcnt(0)
	v_pk_add_f32 v[40:41], v[40:41], v[62:63]
	ds_bpermute_b32 v63, v37, v41
	ds_bpermute_b32 v62, v37, v40
	s_waitcnt lgkmcnt(0)
	v_pk_add_f32 v[40:41], v[40:41], v[62:63]
	s_nop 0
	v_pk_fma_f32 v[40:41], v[40:41], s[10:11], v[186:187] op_sel_hi:[1,1,0]
	s_mov_b32 s10, 0x800000
	v_mul_f32_e32 v62, 0x4b800000, v41
	v_mul_f32_e32 v63, 0x4b800000, v40
	v_cmp_gt_f32_e32 vcc, s10, v41
	v_cmp_gt_f32_e64 s[42:43], s10, v40
	s_mov_b64 s[10:11], 0xe960a00
	v_cndmask_b32_e32 v41, v41, v62, vcc
	v_cndmask_b32_e64 v40, v40, v63, s[42:43]
	v_rsq_f32_e32 v70, v41
	v_rsq_f32_e32 v71, v40
	v_lshl_add_u64 v[40:41], v[24:25], 0, s[16:17]
	v_lshl_add_u64 v[62:63], v[24:25], 0, s[10:11]
	v_mul_f32_e32 v72, 0x45800000, v70
	v_mul_f32_e32 v73, 0x45800000, v71
	v_cndmask_b32_e32 v70, v70, v72, vcc
	v_cndmask_b32_e64 v72, v71, v73, s[42:43]
	v_pk_mul_f32 v[56:57], v[70:71], v[56:57] op_sel_hi:[0,1]
	v_pk_mul_f32 v[42:43], v[72:73], v[42:43] op_sel_hi:[0,1]
	v_pk_mul_f32 v[44:45], v[70:71], v[44:45] op_sel_hi:[0,1]
	v_pk_mul_f32 v[58:59], v[70:71], v[58:59] op_sel_hi:[0,1]
	s_waitcnt vmcnt(4)
	v_pk_mul_f32 v[46:47], v[226:227], v[56:57]
	s_waitcnt vmcnt(1)
	v_pk_mul_f32 v[42:43], v[232:233], v[42:43]
	v_pk_mul_f32 v[44:45], v[228:229], v[44:45]
	v_pk_mul_f32 v[48:49], v[230:231], v[58:59]
	v_cvt_pk_bf16_f32 v46, v46, v47
	v_cvt_pk_bf16_f32 v42, v42, v43
	v_cvt_pk_bf16_f32 v44, v44, v45
	v_cvt_pk_bf16_f32 v45, v48, v49
	global_store_dword v[64:65], v46, off
	global_store_dword v[66:67], v44, off
	global_store_dword v[68:69], v45, off
	global_store_dword v[40:41], v42, off
	v_pk_mul_f32 v[40:41], v[72:73], v[60:61] op_sel_hi:[0,1]
	s_waitcnt vmcnt(4)
	v_pk_mul_f32 v[40:41], v[234:235], v[40:41]
	s_andn2_b64 vcc, exec, s[14:15]
	v_cvt_pk_bf16_f32 v40, v40, v41
	global_store_dword v[62:63], v40, off
	s_cbranch_vccnz .LBB0_161
	v_lshlrev_b32_e32 v42, 16, v28
	v_and_b32_e32 v43, 0xffff0000, v28
	v_mov_b32_e32 v46, v3
	v_mov_b32_e32 v47, v5
	v_lshlrev_b32_e32 v40, 16, v30
	v_and_b32_e32 v41, 0xffff0000, v30
	v_mov_b32_e32 v44, v2
	v_mov_b32_e32 v45, v4
	v_pk_mul_f32 v[48:49], v[46:47], v[42:43]
	s_mov_b32 s10, 0xe960000
	v_pk_fma_f32 v[48:49], v[44:45], v[40:41], v[48:49] neg_lo:[0,0,1] neg_hi:[0,0,1]
	v_pk_mul_f32 v[42:43], v[44:45], v[42:43]
	v_cvt_pk_bf16_f32 v50, v48, v49
	v_add_co_u32_e32 v48, vcc, s10, v26
	v_pk_fma_f32 v[40:41], v[46:47], v[40:41], v[42:43]
	s_nop 0
	v_addc_co_u32_e32 v49, vcc, 0, v27, vcc
	v_cvt_pk_bf16_f32 v40, v40, v41
	v_lshlrev_b32_e32 v42, 16, v29
	v_and_b32_e32 v43, 0xffff0000, v29
	v_mov_b32_e32 v44, v6
	v_mov_b32_e32 v45, v8
	v_mov_b32_e32 v46, v7
	v_mov_b32_e32 v47, v9
	global_store_dword v[48:49], v50, off offset:3840
	global_store_dword v[48:49], v40, off offset:3904
	v_lshlrev_b32_e32 v40, 16, v31
	v_and_b32_e32 v41, 0xffff0000, v31
	v_pk_mul_f32 v[48:49], v[46:47], v[42:43]
	v_pk_mul_f32 v[42:43], v[44:45], v[42:43]
	v_pk_fma_f32 v[48:49], v[44:45], v[40:41], v[48:49] neg_lo:[0,0,1] neg_hi:[0,0,1]
	v_add_co_u32_e32 v26, vcc, 0xe961000, v26
	v_pk_fma_f32 v[40:41], v[46:47], v[40:41], v[42:43]
	v_cvt_pk_bf16_f32 v48, v48, v49
	v_addc_co_u32_e32 v27, vcc, 0, v27, vcc
	v_cvt_pk_bf16_f32 v40, v40, v41
	global_store_dword v[26:27], v48, off offset:256
	global_store_dword v[26:27], v40, off offset:320
	s_and_saveexec_b64 s[14:15], s[40:41]
	s_cbranch_execz .LBB0_160
	v_lshlrev_b32_e32 v26, 16, v39
	v_and_b32_e32 v27, 0xffff0000, v39
	v_lshlrev_b32_e32 v40, 16, v38
	v_and_b32_e32 v41, 0xffff0000, v38
	v_mov_b32_e32 v39, v12
	v_mov_b32_e32 v12, v11
	v_mov_b32_e32 v38, v10
	v_pk_mul_f32 v[10:11], v[12:13], v[40:41]
	v_pk_mul_f32 v[12:13], v[12:13], v[26:27]
	v_pk_fma_f32 v[10:11], v[38:39], v[26:27], v[10:11] neg_lo:[0,0,1] neg_hi:[0,0,1]
	v_pk_fma_f32 v[12:13], v[38:39], v[40:41], v[12:13]
	v_cvt_pk_bf16_f32 v42, v10, v11
	v_add_co_u32_e32 v10, vcc, 0xe961000, v24
	v_cvt_pk_bf16_f32 v12, v12, v13
	s_nop 0
	v_addc_co_u32_e32 v11, vcc, 0, v25, vcc
	global_store_dword v[10:11], v42, off offset:1792
	global_store_dword v[10:11], v12, off offset:1824
	s_branch .LBB0_160
